# pass C step loop fully DPP row_newbcast based (LDS-light), pass A hybrid packed+DPP, hoisted prologue loads, step loops at setprio 1
# speedup vs baseline: 1.0182x; 1.0006x over previous
; #define GAS __attribute__((address_space(1)))
; #define LAS __attribute__((address_space(3)))
; #define LDS_WAIT() asm volatile("s_waitcnt lgkmcnt(0)" ::: "memory")
; #define lane LANE_()
; template <int MODE>
; __device__ __forceinline__ void scan_item(const CAS Args* A, int l, int item, float* slab0, LAS float* ldsw, int lane) {
;     ...
;         LDS_WAIT();
;         float nw[1], nb[1], nk[1], nv[1];
;         { const LAS float* xl = ldsw + 2048 + lane; nw[0] = 0.f; nb[0] = 0.f; nk[0] = 0.f; nv[0] = 0.f; if (MODE != 1) { nk[0] = xl[128]; nv[0] = xl[192]; } }
; #pragma nounroll
;         for (int st = 0; st < 16; ++st) {
;             const int s = d ? 15 - st : st;
;             const float cw = nw[0], cb = nb[0], ck = nk[0], vv = nv[0];
;             if (st < 15) { const GAS float* p = sl + (d ? s - 1 : s + 1) * 384;  if (MODE != 1) { nk[0] = p[192]; nv[0] = p[320]; } }
;             const LAS f32x4* ua = (const LAS f32x4*)(ldsw + s * 64); const LAS f32x4* ur = (const LAS f32x4*)(ldsw + 1024 + s * 64); const LAS f32x4* uw = (const LAS f32x4*)(ldsw + 3072 + s * 64); const LAS f32x4* ub = (const LAS f32x4*)(ldsw + (MODE == 3 ? 1024 : 4096) + s * 64);
;             f2 sa2 = (f2){0.f, 0.f}, sb2 = (f2){0.f, 0.f}, pa2 = (f2){0.f, 0.f}, pb2 = (f2){0.f, 0.f};
; #pragma unroll
;             for (int j = 0; j < 16; ++j) { const f32x4 aq = ua[j]; const f2 a0 = (f2){aq.x, aq.y}, a1 = (f2){aq.z, aq.w}; sa2 = S[2 * j] * a0 + sa2; sb2 = S[2 * j + 1] * a1 + sb2;
;                 if (MODE == 3) { pa2 = Pm[2 * j] * a0 + pa2; pb2 = Pm[2 * j + 1] * a1 + pb2; } }
;             const float sa = (sa2.x + sa2.y) + (sb2.x + sb2.y), pa = (pa2.x + pa2.y) + (pb2.x + pb2.y); const f2 pas = (f2){pa, pa};
.LBB0_551:
	s_or_b64 exec, exec, s[4:5]
	s_waitcnt lgkmcnt(0)
	s_waitcnt lgkmcnt(0)
	v_subrev_u32_e32 v106, s94, v129
	v_and_b32_e32 v98, 60, v106
	v_add_u32_e32 v98, s94, v98
	v_and_b32_e32 v106, 0xc0, v106
	v_sub_u32_e32 v102, 0, v106
	v_ashrrev_i32_e32 v103, 31, v102
	v_lshl_add_u64 v[102:103], v[102:103], 0, v[134:135]
	s_and_b64 s[24:25], s[82:83], exec
	s_cselect_b32 s14, 0, 15
	s_lshl_b32 s8, s14, 8
	v_add_u32_e32 v99, s8, v98
	ds_read_b32 v64, v99 offset:0
	ds_read_b32 v65, v99 offset:64
	ds_read_b32 v66, v99 offset:128
	ds_read_b32 v67, v99 offset:192
	ds_read_b32 v76, v98 offset:8704
	ds_read_b32 v77, v98 offset:8768
	ds_read_b32 v78, v98 offset:8832
	ds_read_b32 v79, v98 offset:8896
	ds_read_b32 v88, v129 offset:8960
	s_waitcnt lgkmcnt(0)
	ds_read_b32 v68, v99 offset:12288
	ds_read_b32 v72, v99 offset:16384
	ds_read_b32 v80, v99 offset:4096
	ds_read_b32 v69, v99 offset:12352
	ds_read_b32 v73, v99 offset:16448
	ds_read_b32 v81, v99 offset:4160
	ds_read_b32 v70, v99 offset:12416
	ds_read_b32 v74, v99 offset:16512
	ds_read_b32 v82, v99 offset:4224
	ds_read_b32 v71, v99 offset:12480
	ds_read_b32 v75, v99 offset:16576
	ds_read_b32 v83, v99 offset:4288
	s_mov_b32 s4, 0
	s_mov_b32 s5, 15
	s_setprio 1
.Lscan_c_step:
	s_and_b64 s[24:25], s[82:83], exec
	s_cselect_b32 s14, s4, s5
	s_add_i32 s8, s14, s27
	s_max_i32 s8, s8, 0
	s_min_i32 s8, s8, 15
	s_lshl_b32 s9, s8, 8
	v_add_u32_e32 v100, s9, v98
	s_mul_i32 s24, s8, 0x600
	s_ashr_i32 s25, s24, 31
	v_lshl_add_u64 v[104:105], v[102:103], 0, s[24:25]
	global_load_dword v84, v[104:105], off offset:768
	global_load_dword v85, v[104:105], off offset:832
	global_load_dword v86, v[104:105], off offset:896
	global_load_dword v87, v[104:105], off offset:960
	s_nop 0
	v_lshl_add_u64 v[104:105], v[134:135], 0, s[24:25]
	global_load_dword v89, v[104:105], off offset:1280
	s_waitcnt lgkmcnt(12)
	v_mul_f32_dpp v90, v64, v12 row_newbcast:0 row_mask:0xf bank_mask:0xf
	v_mul_f32_dpp v91, v64, v13 row_newbcast:1 row_mask:0xf bank_mask:0xf
	v_mul_f32_dpp v92, v64, v14 row_newbcast:2 row_mask:0xf bank_mask:0xf
	v_mul_f32_dpp v93, v64, v15 row_newbcast:3 row_mask:0xf bank_mask:0xf
	v_fmac_f32_dpp v90, v64, v8 row_newbcast:4 row_mask:0xf bank_mask:0xf
	v_fmac_f32_dpp v91, v64, v9 row_newbcast:5 row_mask:0xf bank_mask:0xf
	v_fmac_f32_dpp v92, v64, v10 row_newbcast:6 row_mask:0xf bank_mask:0xf
	v_fmac_f32_dpp v93, v64, v11 row_newbcast:7 row_mask:0xf bank_mask:0xf
	v_fmac_f32_dpp v90, v64, v4 row_newbcast:8 row_mask:0xf bank_mask:0xf
	v_fmac_f32_dpp v91, v64, v5 row_newbcast:9 row_mask:0xf bank_mask:0xf
	v_fmac_f32_dpp v92, v64, v6 row_newbcast:10 row_mask:0xf bank_mask:0xf
	v_fmac_f32_dpp v93, v64, v7 row_newbcast:11 row_mask:0xf bank_mask:0xf
	v_fmac_f32_dpp v90, v64, v0 row_newbcast:12 row_mask:0xf bank_mask:0xf
	v_fmac_f32_dpp v91, v64, v1 row_newbcast:13 row_mask:0xf bank_mask:0xf
	v_fmac_f32_dpp v92, v64, v2 row_newbcast:14 row_mask:0xf bank_mask:0xf
	v_fmac_f32_dpp v93, v64, v3 row_newbcast:15 row_mask:0xf bank_mask:0xf
	v_fmac_f32_dpp v90, v65, v28 row_newbcast:0 row_mask:0xf bank_mask:0xf
	v_fmac_f32_dpp v91, v65, v29 row_newbcast:1 row_mask:0xf bank_mask:0xf
	v_fmac_f32_dpp v92, v65, v30 row_newbcast:2 row_mask:0xf bank_mask:0xf
	v_fmac_f32_dpp v93, v65, v31 row_newbcast:3 row_mask:0xf bank_mask:0xf
	v_fmac_f32_dpp v90, v65, v24 row_newbcast:4 row_mask:0xf bank_mask:0xf
	v_fmac_f32_dpp v91, v65, v25 row_newbcast:5 row_mask:0xf bank_mask:0xf
	v_fmac_f32_dpp v92, v65, v26 row_newbcast:6 row_mask:0xf bank_mask:0xf
	v_fmac_f32_dpp v93, v65, v27 row_newbcast:7 row_mask:0xf bank_mask:0xf
	v_fmac_f32_dpp v90, v65, v20 row_newbcast:8 row_mask:0xf bank_mask:0xf
	v_fmac_f32_dpp v91, v65, v21 row_newbcast:9 row_mask:0xf bank_mask:0xf
	v_fmac_f32_dpp v92, v65, v22 row_newbcast:10 row_mask:0xf bank_mask:0xf
	v_fmac_f32_dpp v93, v65, v23 row_newbcast:11 row_mask:0xf bank_mask:0xf
	v_fmac_f32_dpp v90, v65, v16 row_newbcast:12 row_mask:0xf bank_mask:0xf
	v_fmac_f32_dpp v91, v65, v17 row_newbcast:13 row_mask:0xf bank_mask:0xf
	v_fmac_f32_dpp v92, v65, v18 row_newbcast:14 row_mask:0xf bank_mask:0xf
	v_fmac_f32_dpp v93, v65, v19 row_newbcast:15 row_mask:0xf bank_mask:0xf
	v_fmac_f32_dpp v90, v66, v44 row_newbcast:0 row_mask:0xf bank_mask:0xf
	v_fmac_f32_dpp v91, v66, v45 row_newbcast:1 row_mask:0xf bank_mask:0xf
	v_fmac_f32_dpp v92, v66, v46 row_newbcast:2 row_mask:0xf bank_mask:0xf
	v_fmac_f32_dpp v93, v66, v47 row_newbcast:3 row_mask:0xf bank_mask:0xf
	v_fmac_f32_dpp v90, v66, v40 row_newbcast:4 row_mask:0xf bank_mask:0xf
	v_fmac_f32_dpp v91, v66, v41 row_newbcast:5 row_mask:0xf bank_mask:0xf
	v_fmac_f32_dpp v92, v66, v42 row_newbcast:6 row_mask:0xf bank_mask:0xf
	v_fmac_f32_dpp v93, v66, v43 row_newbcast:7 row_mask:0xf bank_mask:0xf
	v_fmac_f32_dpp v90, v66, v36 row_newbcast:8 row_mask:0xf bank_mask:0xf
	v_fmac_f32_dpp v91, v66, v37 row_newbcast:9 row_mask:0xf bank_mask:0xf
	v_fmac_f32_dpp v92, v66, v38 row_newbcast:10 row_mask:0xf bank_mask:0xf
	v_fmac_f32_dpp v93, v66, v39 row_newbcast:11 row_mask:0xf bank_mask:0xf
	v_fmac_f32_dpp v90, v66, v32 row_newbcast:12 row_mask:0xf bank_mask:0xf
	v_fmac_f32_dpp v91, v66, v33 row_newbcast:13 row_mask:0xf bank_mask:0xf
	v_fmac_f32_dpp v92, v66, v34 row_newbcast:14 row_mask:0xf bank_mask:0xf
	v_fmac_f32_dpp v93, v66, v35 row_newbcast:15 row_mask:0xf bank_mask:0xf
	v_fmac_f32_dpp v90, v67, v60 row_newbcast:0 row_mask:0xf bank_mask:0xf
	v_fmac_f32_dpp v91, v67, v61 row_newbcast:1 row_mask:0xf bank_mask:0xf
	v_fmac_f32_dpp v92, v67, v62 row_newbcast:2 row_mask:0xf bank_mask:0xf
	v_fmac_f32_dpp v93, v67, v63 row_newbcast:3 row_mask:0xf bank_mask:0xf
	v_fmac_f32_dpp v90, v67, v56 row_newbcast:4 row_mask:0xf bank_mask:0xf
	v_fmac_f32_dpp v91, v67, v57 row_newbcast:5 row_mask:0xf bank_mask:0xf
	v_fmac_f32_dpp v92, v67, v58 row_newbcast:6 row_mask:0xf bank_mask:0xf
	v_fmac_f32_dpp v93, v67, v59 row_newbcast:7 row_mask:0xf bank_mask:0xf
	v_fmac_f32_dpp v90, v67, v52 row_newbcast:8 row_mask:0xf bank_mask:0xf
	v_fmac_f32_dpp v91, v67, v53 row_newbcast:9 row_mask:0xf bank_mask:0xf
	v_fmac_f32_dpp v92, v67, v54 row_newbcast:10 row_mask:0xf bank_mask:0xf
	v_fmac_f32_dpp v93, v67, v55 row_newbcast:11 row_mask:0xf bank_mask:0xf
	v_fmac_f32_dpp v90, v67, v48 row_newbcast:12 row_mask:0xf bank_mask:0xf
	v_fmac_f32_dpp v91, v67, v49 row_newbcast:13 row_mask:0xf bank_mask:0xf
	v_fmac_f32_dpp v92, v67, v50 row_newbcast:14 row_mask:0xf bank_mask:0xf
	v_fmac_f32_dpp v93, v67, v51 row_newbcast:15 row_mask:0xf bank_mask:0xf
	v_add_f32_e32 v90, v90, v91
	v_add_f32_e32 v92, v92, v93
	s_waitcnt lgkmcnt(0)
; template <int MODE>
; __device__ __forceinline__ void scan_item(const CAS Args* A, int l, int item, float* slab0, LAS float* ldsw, int lane) {
;     ...
;             for (int j = 0; j < 16; ++j) { const f32x4 aq = ua[j]; const f2 a0 = (f2){aq.x, aq.y}, a1 = (f2){aq.z, aq.w}; sa2 = S[2 * j] * a0 + sa2; sb2 = S[2 * j + 1] * a1 + sb2;
;                 if (MODE == 3) { pa2 = Pm[2 * j] * a0 + pa2; pb2 = Pm[2 * j + 1] * a1 + pb2; } }
;             const float sa = (sa2.x + sa2.y) + (sb2.x + sb2.y), pa = (pa2.x + pa2.y) + (pb2.x + pb2.y); const f2 pas = (f2){pa, pa};
;             const f2 sas = (f2){sa, sa}, vvs = (f2){vv, vv};
;             f2 y2 = (f2){0.f, 0.f}, y3 = (f2){0.f, 0.f};
;             f32x4 nwq[2], nbq[2], nrq[2];
;             nwq[0] = uw[0]; nwq[1] = uw[1]; nbq[0] = ub[0]; nbq[1] = ub[1]; nrq[0] = (f32x4){0.f, 0.f, 0.f, 0.f}; nrq[1] = nrq[0];
;             if (MODE == 2) { nrq[0] = ur[0]; nrq[1] = ur[1]; }
; #pragma unroll
;             for (int g = 0; g < 8; ++g) {
;                 const f32x4 cwq0 = nwq[0], cwq1 = nwq[1], cbq0 = nbq[0], cbq1 = nbq[1], crq0 = nrq[0], crq1 = nrq[1];
;                 if (g < 7) { nwq[0] = uw[2 * g + 2]; nwq[1] = uw[2 * g + 3]; nbq[0] = ub[2 * g + 2]; nbq[1] = ub[2 * g + 3];
;                     if (MODE == 2) { nrq[0] = ur[2 * g + 2]; nrq[1] = ur[2 * g + 3]; } }
;                 f2 bb[4], ww[4], kq[4], rr[4];
;                 ww[0] = (f2){cwq0.x, cwq0.y}; ww[1] = (f2){cwq0.z, cwq0.w}; ww[2] = (f2){cwq1.x, cwq1.y}; ww[3] = (f2){cwq1.z, cwq1.w};
;                 bb[0] = (f2){cbq0.x, cbq0.y}; bb[1] = (f2){cbq0.z, cbq0.w}; bb[2] = (f2){cbq1.x, cbq1.y}; bb[3] = (f2){cbq1.z, cbq1.w};
;                 rr[0] = (f2){crq0.x, crq0.y}; rr[1] = (f2){crq0.z, crq0.w}; rr[2] = (f2){crq1.x, crq1.y}; rr[3] = (f2){crq1.z, crq1.w};
; #pragma unroll
;                 for (int q = 0; q < 4; ++q) { const int j = g * 4 + q; if (MODE != 1) kq[q] = RL2(ck, j); }
;                 __builtin_amdgcn_sched_barrier(0);
; #pragma unroll
;                 for (int q = 0; q < 4; ++q) { const int j = g * 4 + q;
;                     f2 t = sas * bb[q];
;                     if (MODE != 1) t = vvs * kq[q] + t;
;                     S[j] = S[j] * ww[q] + t;
;                     if (MODE == 3) Pm[j] = Pm[j] * ww[q] + pas * bb[q];
;                     if (MODE == 2) { if (j & 1) y3 = S[j] * rr[q] + y3; else y2 = S[j] * rr[q] + y2; } }
	ds_read_b32 v64, v100 offset:0
	ds_read_b32 v65, v100 offset:64
	ds_read_b32 v66, v100 offset:128
	ds_read_b32 v67, v100 offset:192
	v_add_f32_e32 v90, v90, v92
	v_mul_f32_dpp v12, v68, v12 row_newbcast:0 row_mask:0xf bank_mask:0xf
	v_mul_f32_dpp v13, v68, v13 row_newbcast:1 row_mask:0xf bank_mask:0xf
	v_mul_f32_dpp v14, v68, v14 row_newbcast:2 row_mask:0xf bank_mask:0xf
	v_mul_f32_dpp v15, v68, v15 row_newbcast:3 row_mask:0xf bank_mask:0xf
	v_fmac_f32_dpp v12, v72, v90 row_newbcast:0 row_mask:0xf bank_mask:0xf
	v_fmac_f32_dpp v13, v72, v90 row_newbcast:1 row_mask:0xf bank_mask:0xf
	v_fmac_f32_dpp v14, v72, v90 row_newbcast:2 row_mask:0xf bank_mask:0xf
	v_fmac_f32_dpp v15, v72, v90 row_newbcast:3 row_mask:0xf bank_mask:0xf
	v_fmac_f32_dpp v12, v76, v88 row_newbcast:0 row_mask:0xf bank_mask:0xf
	v_fmac_f32_dpp v13, v76, v88 row_newbcast:1 row_mask:0xf bank_mask:0xf
	v_fmac_f32_dpp v14, v76, v88 row_newbcast:2 row_mask:0xf bank_mask:0xf
	v_fmac_f32_dpp v15, v76, v88 row_newbcast:3 row_mask:0xf bank_mask:0xf
	v_mul_f32_dpp v94, v80, v12 row_newbcast:0 row_mask:0xf bank_mask:0xf
	v_mul_f32_dpp v95, v80, v13 row_newbcast:1 row_mask:0xf bank_mask:0xf
	v_mul_f32_dpp v96, v80, v14 row_newbcast:2 row_mask:0xf bank_mask:0xf
	v_mul_f32_dpp v97, v80, v15 row_newbcast:3 row_mask:0xf bank_mask:0xf
	v_mul_f32_dpp v8, v68, v8 row_newbcast:4 row_mask:0xf bank_mask:0xf
	v_mul_f32_dpp v9, v68, v9 row_newbcast:5 row_mask:0xf bank_mask:0xf
	v_mul_f32_dpp v10, v68, v10 row_newbcast:6 row_mask:0xf bank_mask:0xf
	v_mul_f32_dpp v11, v68, v11 row_newbcast:7 row_mask:0xf bank_mask:0xf
	v_fmac_f32_dpp v8, v72, v90 row_newbcast:4 row_mask:0xf bank_mask:0xf
	v_fmac_f32_dpp v9, v72, v90 row_newbcast:5 row_mask:0xf bank_mask:0xf
	v_fmac_f32_dpp v10, v72, v90 row_newbcast:6 row_mask:0xf bank_mask:0xf
	v_fmac_f32_dpp v11, v72, v90 row_newbcast:7 row_mask:0xf bank_mask:0xf
	v_fmac_f32_dpp v8, v76, v88 row_newbcast:4 row_mask:0xf bank_mask:0xf
	v_fmac_f32_dpp v9, v76, v88 row_newbcast:5 row_mask:0xf bank_mask:0xf
	v_fmac_f32_dpp v10, v76, v88 row_newbcast:6 row_mask:0xf bank_mask:0xf
	v_fmac_f32_dpp v11, v76, v88 row_newbcast:7 row_mask:0xf bank_mask:0xf
	v_fmac_f32_dpp v94, v80, v8 row_newbcast:4 row_mask:0xf bank_mask:0xf
	v_fmac_f32_dpp v95, v80, v9 row_newbcast:5 row_mask:0xf bank_mask:0xf
	v_fmac_f32_dpp v96, v80, v10 row_newbcast:6 row_mask:0xf bank_mask:0xf
	v_fmac_f32_dpp v97, v80, v11 row_newbcast:7 row_mask:0xf bank_mask:0xf
	v_mul_f32_dpp v4, v68, v4 row_newbcast:8 row_mask:0xf bank_mask:0xf
	v_mul_f32_dpp v5, v68, v5 row_newbcast:9 row_mask:0xf bank_mask:0xf
	v_mul_f32_dpp v6, v68, v6 row_newbcast:10 row_mask:0xf bank_mask:0xf
	v_mul_f32_dpp v7, v68, v7 row_newbcast:11 row_mask:0xf bank_mask:0xf
	v_fmac_f32_dpp v4, v72, v90 row_newbcast:8 row_mask:0xf bank_mask:0xf
	v_fmac_f32_dpp v5, v72, v90 row_newbcast:9 row_mask:0xf bank_mask:0xf
	v_fmac_f32_dpp v6, v72, v90 row_newbcast:10 row_mask:0xf bank_mask:0xf
	v_fmac_f32_dpp v7, v72, v90 row_newbcast:11 row_mask:0xf bank_mask:0xf
	v_fmac_f32_dpp v4, v76, v88 row_newbcast:8 row_mask:0xf bank_mask:0xf
	v_fmac_f32_dpp v5, v76, v88 row_newbcast:9 row_mask:0xf bank_mask:0xf
	v_fmac_f32_dpp v6, v76, v88 row_newbcast:10 row_mask:0xf bank_mask:0xf
	v_fmac_f32_dpp v7, v76, v88 row_newbcast:11 row_mask:0xf bank_mask:0xf
	v_fmac_f32_dpp v94, v80, v4 row_newbcast:8 row_mask:0xf bank_mask:0xf
	v_fmac_f32_dpp v95, v80, v5 row_newbcast:9 row_mask:0xf bank_mask:0xf
	v_fmac_f32_dpp v96, v80, v6 row_newbcast:10 row_mask:0xf bank_mask:0xf
	v_fmac_f32_dpp v97, v80, v7 row_newbcast:11 row_mask:0xf bank_mask:0xf
	v_mul_f32_dpp v0, v68, v0 row_newbcast:12 row_mask:0xf bank_mask:0xf
	v_mul_f32_dpp v1, v68, v1 row_newbcast:13 row_mask:0xf bank_mask:0xf
	v_mul_f32_dpp v2, v68, v2 row_newbcast:14 row_mask:0xf bank_mask:0xf
	v_mul_f32_dpp v3, v68, v3 row_newbcast:15 row_mask:0xf bank_mask:0xf
	v_fmac_f32_dpp v0, v72, v90 row_newbcast:12 row_mask:0xf bank_mask:0xf
	v_fmac_f32_dpp v1, v72, v90 row_newbcast:13 row_mask:0xf bank_mask:0xf
	v_fmac_f32_dpp v2, v72, v90 row_newbcast:14 row_mask:0xf bank_mask:0xf
	v_fmac_f32_dpp v3, v72, v90 row_newbcast:15 row_mask:0xf bank_mask:0xf
	v_fmac_f32_dpp v0, v76, v88 row_newbcast:12 row_mask:0xf bank_mask:0xf
	v_fmac_f32_dpp v1, v76, v88 row_newbcast:13 row_mask:0xf bank_mask:0xf
	v_fmac_f32_dpp v2, v76, v88 row_newbcast:14 row_mask:0xf bank_mask:0xf
	v_fmac_f32_dpp v3, v76, v88 row_newbcast:15 row_mask:0xf bank_mask:0xf
	v_fmac_f32_dpp v94, v80, v0 row_newbcast:12 row_mask:0xf bank_mask:0xf
	v_fmac_f32_dpp v95, v80, v1 row_newbcast:13 row_mask:0xf bank_mask:0xf
	v_fmac_f32_dpp v96, v80, v2 row_newbcast:14 row_mask:0xf bank_mask:0xf
	v_fmac_f32_dpp v97, v80, v3 row_newbcast:15 row_mask:0xf bank_mask:0xf
	ds_read_b32 v68, v100 offset:12288
	ds_read_b32 v72, v100 offset:16384
	ds_read_b32 v80, v100 offset:4096
	v_mul_f32_dpp v28, v69, v28 row_newbcast:0 row_mask:0xf bank_mask:0xf
	v_mul_f32_dpp v29, v69, v29 row_newbcast:1 row_mask:0xf bank_mask:0xf
	v_mul_f32_dpp v30, v69, v30 row_newbcast:2 row_mask:0xf bank_mask:0xf
	v_mul_f32_dpp v31, v69, v31 row_newbcast:3 row_mask:0xf bank_mask:0xf
	v_fmac_f32_dpp v28, v73, v90 row_newbcast:0 row_mask:0xf bank_mask:0xf
	v_fmac_f32_dpp v29, v73, v90 row_newbcast:1 row_mask:0xf bank_mask:0xf
	v_fmac_f32_dpp v30, v73, v90 row_newbcast:2 row_mask:0xf bank_mask:0xf
	v_fmac_f32_dpp v31, v73, v90 row_newbcast:3 row_mask:0xf bank_mask:0xf
	v_fmac_f32_dpp v28, v77, v88 row_newbcast:0 row_mask:0xf bank_mask:0xf
	v_fmac_f32_dpp v29, v77, v88 row_newbcast:1 row_mask:0xf bank_mask:0xf
	v_fmac_f32_dpp v30, v77, v88 row_newbcast:2 row_mask:0xf bank_mask:0xf
; #define RL2(x, j) (f2){__builtin_bit_cast(float, __builtin_amdgcn_readlane(__builtin_bit_cast(int, x), 2 * (j))), __builtin_bit_cast(float, __builtin_amdgcn_readlane(__builtin_bit_cast(int, x), 2 * (j) + 1))}
; template <int MODE>
; __device__ __forceinline__ void scan_item(const CAS Args* A, int l, int item, float* slab0, LAS float* ldsw, int lane) {
;     ...
;             for (int g = 0; g < 8; ++g) {
;                 const f32x4 cwq0 = nwq[0], cwq1 = nwq[1], cbq0 = nbq[0], cbq1 = nbq[1], crq0 = nrq[0], crq1 = nrq[1];
;                 if (g < 7) { nwq[0] = uw[2 * g + 2]; nwq[1] = uw[2 * g + 3]; nbq[0] = ub[2 * g + 2]; nbq[1] = ub[2 * g + 3];
;                     if (MODE == 2) { nrq[0] = ur[2 * g + 2]; nrq[1] = ur[2 * g + 3]; } }
;                 f2 bb[4], ww[4], kq[4], rr[4];
;                 ww[0] = (f2){cwq0.x, cwq0.y}; ww[1] = (f2){cwq0.z, cwq0.w}; ww[2] = (f2){cwq1.x, cwq1.y}; ww[3] = (f2){cwq1.z, cwq1.w};
;                 bb[0] = (f2){cbq0.x, cbq0.y}; bb[1] = (f2){cbq0.z, cbq0.w}; bb[2] = (f2){cbq1.x, cbq1.y}; bb[3] = (f2){cbq1.z, cbq1.w};
;                 rr[0] = (f2){crq0.x, crq0.y}; rr[1] = (f2){crq0.z, crq0.w}; rr[2] = (f2){crq1.x, crq1.y}; rr[3] = (f2){crq1.z, crq1.w};
; #pragma unroll
;                 for (int q = 0; q < 4; ++q) { const int j = g * 4 + q; if (MODE != 1) kq[q] = RL2(ck, j); }
;                 __builtin_amdgcn_sched_barrier(0);
; #pragma unroll
;                 for (int q = 0; q < 4; ++q) { const int j = g * 4 + q;
;                     f2 t = sas * bb[q];
;                     if (MODE != 1) t = vvs * kq[q] + t;
;                     S[j] = S[j] * ww[q] + t;
;                     if (MODE == 3) Pm[j] = Pm[j] * ww[q] + pas * bb[q];
;                     if (MODE == 2) { if (j & 1) y3 = S[j] * rr[q] + y3; else y2 = S[j] * rr[q] + y2; } }
	v_fmac_f32_dpp v31, v77, v88 row_newbcast:3 row_mask:0xf bank_mask:0xf
	v_fmac_f32_dpp v94, v81, v28 row_newbcast:0 row_mask:0xf bank_mask:0xf
	v_fmac_f32_dpp v95, v81, v29 row_newbcast:1 row_mask:0xf bank_mask:0xf
	v_fmac_f32_dpp v96, v81, v30 row_newbcast:2 row_mask:0xf bank_mask:0xf
	v_fmac_f32_dpp v97, v81, v31 row_newbcast:3 row_mask:0xf bank_mask:0xf
	v_mul_f32_dpp v24, v69, v24 row_newbcast:4 row_mask:0xf bank_mask:0xf
	v_mul_f32_dpp v25, v69, v25 row_newbcast:5 row_mask:0xf bank_mask:0xf
	v_mul_f32_dpp v26, v69, v26 row_newbcast:6 row_mask:0xf bank_mask:0xf
	v_mul_f32_dpp v27, v69, v27 row_newbcast:7 row_mask:0xf bank_mask:0xf
	v_fmac_f32_dpp v24, v73, v90 row_newbcast:4 row_mask:0xf bank_mask:0xf
	v_fmac_f32_dpp v25, v73, v90 row_newbcast:5 row_mask:0xf bank_mask:0xf
	v_fmac_f32_dpp v26, v73, v90 row_newbcast:6 row_mask:0xf bank_mask:0xf
	v_fmac_f32_dpp v27, v73, v90 row_newbcast:7 row_mask:0xf bank_mask:0xf
	v_fmac_f32_dpp v24, v77, v88 row_newbcast:4 row_mask:0xf bank_mask:0xf
	v_fmac_f32_dpp v25, v77, v88 row_newbcast:5 row_mask:0xf bank_mask:0xf
	v_fmac_f32_dpp v26, v77, v88 row_newbcast:6 row_mask:0xf bank_mask:0xf
	v_fmac_f32_dpp v27, v77, v88 row_newbcast:7 row_mask:0xf bank_mask:0xf
	v_fmac_f32_dpp v94, v81, v24 row_newbcast:4 row_mask:0xf bank_mask:0xf
	v_fmac_f32_dpp v95, v81, v25 row_newbcast:5 row_mask:0xf bank_mask:0xf
	v_fmac_f32_dpp v96, v81, v26 row_newbcast:6 row_mask:0xf bank_mask:0xf
	v_fmac_f32_dpp v97, v81, v27 row_newbcast:7 row_mask:0xf bank_mask:0xf
	v_mul_f32_dpp v20, v69, v20 row_newbcast:8 row_mask:0xf bank_mask:0xf
	v_mul_f32_dpp v21, v69, v21 row_newbcast:9 row_mask:0xf bank_mask:0xf
	v_mul_f32_dpp v22, v69, v22 row_newbcast:10 row_mask:0xf bank_mask:0xf
	v_mul_f32_dpp v23, v69, v23 row_newbcast:11 row_mask:0xf bank_mask:0xf
	v_fmac_f32_dpp v20, v73, v90 row_newbcast:8 row_mask:0xf bank_mask:0xf
	v_fmac_f32_dpp v21, v73, v90 row_newbcast:9 row_mask:0xf bank_mask:0xf
	v_fmac_f32_dpp v22, v73, v90 row_newbcast:10 row_mask:0xf bank_mask:0xf
	v_fmac_f32_dpp v23, v73, v90 row_newbcast:11 row_mask:0xf bank_mask:0xf
	v_fmac_f32_dpp v20, v77, v88 row_newbcast:8 row_mask:0xf bank_mask:0xf
	v_fmac_f32_dpp v21, v77, v88 row_newbcast:9 row_mask:0xf bank_mask:0xf
	v_fmac_f32_dpp v22, v77, v88 row_newbcast:10 row_mask:0xf bank_mask:0xf
	v_fmac_f32_dpp v23, v77, v88 row_newbcast:11 row_mask:0xf bank_mask:0xf
	v_fmac_f32_dpp v94, v81, v20 row_newbcast:8 row_mask:0xf bank_mask:0xf
	v_fmac_f32_dpp v95, v81, v21 row_newbcast:9 row_mask:0xf bank_mask:0xf
	v_fmac_f32_dpp v96, v81, v22 row_newbcast:10 row_mask:0xf bank_mask:0xf
	v_fmac_f32_dpp v97, v81, v23 row_newbcast:11 row_mask:0xf bank_mask:0xf
	v_mul_f32_dpp v16, v69, v16 row_newbcast:12 row_mask:0xf bank_mask:0xf
	v_mul_f32_dpp v17, v69, v17 row_newbcast:13 row_mask:0xf bank_mask:0xf
	v_mul_f32_dpp v18, v69, v18 row_newbcast:14 row_mask:0xf bank_mask:0xf
	v_mul_f32_dpp v19, v69, v19 row_newbcast:15 row_mask:0xf bank_mask:0xf
	v_fmac_f32_dpp v16, v73, v90 row_newbcast:12 row_mask:0xf bank_mask:0xf
	v_fmac_f32_dpp v17, v73, v90 row_newbcast:13 row_mask:0xf bank_mask:0xf
	v_fmac_f32_dpp v18, v73, v90 row_newbcast:14 row_mask:0xf bank_mask:0xf
	v_fmac_f32_dpp v19, v73, v90 row_newbcast:15 row_mask:0xf bank_mask:0xf
	v_fmac_f32_dpp v16, v77, v88 row_newbcast:12 row_mask:0xf bank_mask:0xf
	v_fmac_f32_dpp v17, v77, v88 row_newbcast:13 row_mask:0xf bank_mask:0xf
	v_fmac_f32_dpp v18, v77, v88 row_newbcast:14 row_mask:0xf bank_mask:0xf
	v_fmac_f32_dpp v19, v77, v88 row_newbcast:15 row_mask:0xf bank_mask:0xf
	v_fmac_f32_dpp v94, v81, v16 row_newbcast:12 row_mask:0xf bank_mask:0xf
	v_fmac_f32_dpp v95, v81, v17 row_newbcast:13 row_mask:0xf bank_mask:0xf
	v_fmac_f32_dpp v96, v81, v18 row_newbcast:14 row_mask:0xf bank_mask:0xf
	v_fmac_f32_dpp v97, v81, v19 row_newbcast:15 row_mask:0xf bank_mask:0xf
	ds_read_b32 v69, v100 offset:12352
	ds_read_b32 v73, v100 offset:16448
	ds_read_b32 v81, v100 offset:4160
	v_mul_f32_dpp v44, v70, v44 row_newbcast:0 row_mask:0xf bank_mask:0xf
	v_mul_f32_dpp v45, v70, v45 row_newbcast:1 row_mask:0xf bank_mask:0xf
	v_mul_f32_dpp v46, v70, v46 row_newbcast:2 row_mask:0xf bank_mask:0xf
	v_mul_f32_dpp v47, v70, v47 row_newbcast:3 row_mask:0xf bank_mask:0xf
	v_fmac_f32_dpp v44, v74, v90 row_newbcast:0 row_mask:0xf bank_mask:0xf
	v_fmac_f32_dpp v45, v74, v90 row_newbcast:1 row_mask:0xf bank_mask:0xf
	v_fmac_f32_dpp v46, v74, v90 row_newbcast:2 row_mask:0xf bank_mask:0xf
	v_fmac_f32_dpp v47, v74, v90 row_newbcast:3 row_mask:0xf bank_mask:0xf
	v_fmac_f32_dpp v44, v78, v88 row_newbcast:0 row_mask:0xf bank_mask:0xf
	v_fmac_f32_dpp v45, v78, v88 row_newbcast:1 row_mask:0xf bank_mask:0xf
	v_fmac_f32_dpp v46, v78, v88 row_newbcast:2 row_mask:0xf bank_mask:0xf
	v_fmac_f32_dpp v47, v78, v88 row_newbcast:3 row_mask:0xf bank_mask:0xf
	v_fmac_f32_dpp v94, v82, v44 row_newbcast:0 row_mask:0xf bank_mask:0xf
	v_fmac_f32_dpp v95, v82, v45 row_newbcast:1 row_mask:0xf bank_mask:0xf
	v_fmac_f32_dpp v96, v82, v46 row_newbcast:2 row_mask:0xf bank_mask:0xf
	v_fmac_f32_dpp v97, v82, v47 row_newbcast:3 row_mask:0xf bank_mask:0xf
	v_mul_f32_dpp v40, v70, v40 row_newbcast:4 row_mask:0xf bank_mask:0xf
	v_mul_f32_dpp v41, v70, v41 row_newbcast:5 row_mask:0xf bank_mask:0xf
	v_mul_f32_dpp v42, v70, v42 row_newbcast:6 row_mask:0xf bank_mask:0xf
	v_mul_f32_dpp v43, v70, v43 row_newbcast:7 row_mask:0xf bank_mask:0xf
	v_fmac_f32_dpp v40, v74, v90 row_newbcast:4 row_mask:0xf bank_mask:0xf
	v_fmac_f32_dpp v41, v74, v90 row_newbcast:5 row_mask:0xf bank_mask:0xf
	v_fmac_f32_dpp v42, v74, v90 row_newbcast:6 row_mask:0xf bank_mask:0xf
	v_fmac_f32_dpp v43, v74, v90 row_newbcast:7 row_mask:0xf bank_mask:0xf
; #define RL2(x, j) (f2){__builtin_bit_cast(float, __builtin_amdgcn_readlane(__builtin_bit_cast(int, x), 2 * (j))), __builtin_bit_cast(float, __builtin_amdgcn_readlane(__builtin_bit_cast(int, x), 2 * (j) + 1))}
; template <int MODE>
; __device__ __forceinline__ void scan_item(const CAS Args* A, int l, int item, float* slab0, LAS float* ldsw, int lane) {
;     ...
;             for (int g = 0; g < 8; ++g) {
;                 const f32x4 cwq0 = nwq[0], cwq1 = nwq[1], cbq0 = nbq[0], cbq1 = nbq[1], crq0 = nrq[0], crq1 = nrq[1];
;                 if (g < 7) { nwq[0] = uw[2 * g + 2]; nwq[1] = uw[2 * g + 3]; nbq[0] = ub[2 * g + 2]; nbq[1] = ub[2 * g + 3];
;                     if (MODE == 2) { nrq[0] = ur[2 * g + 2]; nrq[1] = ur[2 * g + 3]; } }
;                 f2 bb[4], ww[4], kq[4], rr[4];
;                 ww[0] = (f2){cwq0.x, cwq0.y}; ww[1] = (f2){cwq0.z, cwq0.w}; ww[2] = (f2){cwq1.x, cwq1.y}; ww[3] = (f2){cwq1.z, cwq1.w};
;                 bb[0] = (f2){cbq0.x, cbq0.y}; bb[1] = (f2){cbq0.z, cbq0.w}; bb[2] = (f2){cbq1.x, cbq1.y}; bb[3] = (f2){cbq1.z, cbq1.w};
;                 rr[0] = (f2){crq0.x, crq0.y}; rr[1] = (f2){crq0.z, crq0.w}; rr[2] = (f2){crq1.x, crq1.y}; rr[3] = (f2){crq1.z, crq1.w};
; #pragma unroll
;                 for (int q = 0; q < 4; ++q) { const int j = g * 4 + q; if (MODE != 1) kq[q] = RL2(ck, j); }
;                 __builtin_amdgcn_sched_barrier(0);
; #pragma unroll
;                 for (int q = 0; q < 4; ++q) { const int j = g * 4 + q;
;                     f2 t = sas * bb[q];
;                     if (MODE != 1) t = vvs * kq[q] + t;
;                     S[j] = S[j] * ww[q] + t;
;                     if (MODE == 3) Pm[j] = Pm[j] * ww[q] + pas * bb[q];
;                     if (MODE == 2) { if (j & 1) y3 = S[j] * rr[q] + y3; else y2 = S[j] * rr[q] + y2; } }
	v_fmac_f32_dpp v40, v78, v88 row_newbcast:4 row_mask:0xf bank_mask:0xf
	v_fmac_f32_dpp v41, v78, v88 row_newbcast:5 row_mask:0xf bank_mask:0xf
	v_fmac_f32_dpp v42, v78, v88 row_newbcast:6 row_mask:0xf bank_mask:0xf
	v_fmac_f32_dpp v43, v78, v88 row_newbcast:7 row_mask:0xf bank_mask:0xf
	v_fmac_f32_dpp v94, v82, v40 row_newbcast:4 row_mask:0xf bank_mask:0xf
	v_fmac_f32_dpp v95, v82, v41 row_newbcast:5 row_mask:0xf bank_mask:0xf
	v_fmac_f32_dpp v96, v82, v42 row_newbcast:6 row_mask:0xf bank_mask:0xf
	v_fmac_f32_dpp v97, v82, v43 row_newbcast:7 row_mask:0xf bank_mask:0xf
	v_mul_f32_dpp v36, v70, v36 row_newbcast:8 row_mask:0xf bank_mask:0xf
	v_mul_f32_dpp v37, v70, v37 row_newbcast:9 row_mask:0xf bank_mask:0xf
	v_mul_f32_dpp v38, v70, v38 row_newbcast:10 row_mask:0xf bank_mask:0xf
	v_mul_f32_dpp v39, v70, v39 row_newbcast:11 row_mask:0xf bank_mask:0xf
	v_fmac_f32_dpp v36, v74, v90 row_newbcast:8 row_mask:0xf bank_mask:0xf
	v_fmac_f32_dpp v37, v74, v90 row_newbcast:9 row_mask:0xf bank_mask:0xf
	v_fmac_f32_dpp v38, v74, v90 row_newbcast:10 row_mask:0xf bank_mask:0xf
	v_fmac_f32_dpp v39, v74, v90 row_newbcast:11 row_mask:0xf bank_mask:0xf
	v_fmac_f32_dpp v36, v78, v88 row_newbcast:8 row_mask:0xf bank_mask:0xf
	v_fmac_f32_dpp v37, v78, v88 row_newbcast:9 row_mask:0xf bank_mask:0xf
	v_fmac_f32_dpp v38, v78, v88 row_newbcast:10 row_mask:0xf bank_mask:0xf
	v_fmac_f32_dpp v39, v78, v88 row_newbcast:11 row_mask:0xf bank_mask:0xf
	v_fmac_f32_dpp v94, v82, v36 row_newbcast:8 row_mask:0xf bank_mask:0xf
	v_fmac_f32_dpp v95, v82, v37 row_newbcast:9 row_mask:0xf bank_mask:0xf
	v_fmac_f32_dpp v96, v82, v38 row_newbcast:10 row_mask:0xf bank_mask:0xf
	v_fmac_f32_dpp v97, v82, v39 row_newbcast:11 row_mask:0xf bank_mask:0xf
	v_mul_f32_dpp v32, v70, v32 row_newbcast:12 row_mask:0xf bank_mask:0xf
	v_mul_f32_dpp v33, v70, v33 row_newbcast:13 row_mask:0xf bank_mask:0xf
	v_mul_f32_dpp v34, v70, v34 row_newbcast:14 row_mask:0xf bank_mask:0xf
	v_mul_f32_dpp v35, v70, v35 row_newbcast:15 row_mask:0xf bank_mask:0xf
	v_fmac_f32_dpp v32, v74, v90 row_newbcast:12 row_mask:0xf bank_mask:0xf
	v_fmac_f32_dpp v33, v74, v90 row_newbcast:13 row_mask:0xf bank_mask:0xf
	v_fmac_f32_dpp v34, v74, v90 row_newbcast:14 row_mask:0xf bank_mask:0xf
	v_fmac_f32_dpp v35, v74, v90 row_newbcast:15 row_mask:0xf bank_mask:0xf
	v_fmac_f32_dpp v32, v78, v88 row_newbcast:12 row_mask:0xf bank_mask:0xf
	v_fmac_f32_dpp v33, v78, v88 row_newbcast:13 row_mask:0xf bank_mask:0xf
	v_fmac_f32_dpp v34, v78, v88 row_newbcast:14 row_mask:0xf bank_mask:0xf
	v_fmac_f32_dpp v35, v78, v88 row_newbcast:15 row_mask:0xf bank_mask:0xf
	v_fmac_f32_dpp v94, v82, v32 row_newbcast:12 row_mask:0xf bank_mask:0xf
	v_fmac_f32_dpp v95, v82, v33 row_newbcast:13 row_mask:0xf bank_mask:0xf
	v_fmac_f32_dpp v96, v82, v34 row_newbcast:14 row_mask:0xf bank_mask:0xf
	v_fmac_f32_dpp v97, v82, v35 row_newbcast:15 row_mask:0xf bank_mask:0xf
	ds_read_b32 v70, v100 offset:12416
	ds_read_b32 v74, v100 offset:16512
	ds_read_b32 v82, v100 offset:4224
	v_mul_f32_dpp v60, v71, v60 row_newbcast:0 row_mask:0xf bank_mask:0xf
	v_mul_f32_dpp v61, v71, v61 row_newbcast:1 row_mask:0xf bank_mask:0xf
	v_mul_f32_dpp v62, v71, v62 row_newbcast:2 row_mask:0xf bank_mask:0xf
	v_mul_f32_dpp v63, v71, v63 row_newbcast:3 row_mask:0xf bank_mask:0xf
	v_fmac_f32_dpp v60, v75, v90 row_newbcast:0 row_mask:0xf bank_mask:0xf
	v_fmac_f32_dpp v61, v75, v90 row_newbcast:1 row_mask:0xf bank_mask:0xf
	v_fmac_f32_dpp v62, v75, v90 row_newbcast:2 row_mask:0xf bank_mask:0xf
	v_fmac_f32_dpp v63, v75, v90 row_newbcast:3 row_mask:0xf bank_mask:0xf
	v_fmac_f32_dpp v60, v79, v88 row_newbcast:0 row_mask:0xf bank_mask:0xf
	v_fmac_f32_dpp v61, v79, v88 row_newbcast:1 row_mask:0xf bank_mask:0xf
	v_fmac_f32_dpp v62, v79, v88 row_newbcast:2 row_mask:0xf bank_mask:0xf
	v_fmac_f32_dpp v63, v79, v88 row_newbcast:3 row_mask:0xf bank_mask:0xf
	v_fmac_f32_dpp v94, v83, v60 row_newbcast:0 row_mask:0xf bank_mask:0xf
	v_fmac_f32_dpp v95, v83, v61 row_newbcast:1 row_mask:0xf bank_mask:0xf
	v_fmac_f32_dpp v96, v83, v62 row_newbcast:2 row_mask:0xf bank_mask:0xf
	v_fmac_f32_dpp v97, v83, v63 row_newbcast:3 row_mask:0xf bank_mask:0xf
; __device__ __forceinline__ unsigned f2bf(float f) { return pk2(f, f) & 0xffffu; }
; #define RL2(x, j) (f2){__builtin_bit_cast(float, __builtin_amdgcn_readlane(__builtin_bit_cast(int, x), 2 * (j))), __builtin_bit_cast(float, __builtin_amdgcn_readlane(__builtin_bit_cast(int, x), 2 * (j) + 1))}
; #define lane LANE_()
; template <int MODE>
; __device__ __forceinline__ void scan_item(const CAS Args* A, int l, int item, float* slab0, LAS float* ldsw, int lane) {
;     ...
;             for (int g = 0; g < 8; ++g) {
;                 const f32x4 cwq0 = nwq[0], cwq1 = nwq[1], cbq0 = nbq[0], cbq1 = nbq[1], crq0 = nrq[0], crq1 = nrq[1];
;                 if (g < 7) { nwq[0] = uw[2 * g + 2]; nwq[1] = uw[2 * g + 3]; nbq[0] = ub[2 * g + 2]; nbq[1] = ub[2 * g + 3];
;                     if (MODE == 2) { nrq[0] = ur[2 * g + 2]; nrq[1] = ur[2 * g + 3]; } }
;                 f2 bb[4], ww[4], kq[4], rr[4];
;                 ww[0] = (f2){cwq0.x, cwq0.y}; ww[1] = (f2){cwq0.z, cwq0.w}; ww[2] = (f2){cwq1.x, cwq1.y}; ww[3] = (f2){cwq1.z, cwq1.w};
;                 bb[0] = (f2){cbq0.x, cbq0.y}; bb[1] = (f2){cbq0.z, cbq0.w}; bb[2] = (f2){cbq1.x, cbq1.y}; bb[3] = (f2){cbq1.z, cbq1.w};
;                 rr[0] = (f2){crq0.x, crq0.y}; rr[1] = (f2){crq0.z, crq0.w}; rr[2] = (f2){crq1.x, crq1.y}; rr[3] = (f2){crq1.z, crq1.w};
; #pragma unroll
;                 for (int q = 0; q < 4; ++q) { const int j = g * 4 + q; if (MODE != 1) kq[q] = RL2(ck, j); }
;                 __builtin_amdgcn_sched_barrier(0);
; #pragma unroll
;                 for (int q = 0; q < 4; ++q) { const int j = g * 4 + q;
;                     f2 t = sas * bb[q];
;                     if (MODE != 1) t = vvs * kq[q] + t;
;                     S[j] = S[j] * ww[q] + t;
;                     if (MODE == 3) Pm[j] = Pm[j] * ww[q] + pas * bb[q];
;                     if (MODE == 2) { if (j & 1) y3 = S[j] * rr[q] + y3; else y2 = S[j] * rr[q] + y2; } }
;             }
;             if (MODE == 2) yb[(size_t)(t0 + s) * 512 + h * 64 + lane] = (bf16)f2bf((y2.x + y2.y) + (y3.x + y3.y));
;         }
	v_mul_f32_dpp v56, v71, v56 row_newbcast:4 row_mask:0xf bank_mask:0xf
	v_mul_f32_dpp v57, v71, v57 row_newbcast:5 row_mask:0xf bank_mask:0xf
	v_mul_f32_dpp v58, v71, v58 row_newbcast:6 row_mask:0xf bank_mask:0xf
	v_mul_f32_dpp v59, v71, v59 row_newbcast:7 row_mask:0xf bank_mask:0xf
	v_fmac_f32_dpp v56, v75, v90 row_newbcast:4 row_mask:0xf bank_mask:0xf
	v_fmac_f32_dpp v57, v75, v90 row_newbcast:5 row_mask:0xf bank_mask:0xf
	v_fmac_f32_dpp v58, v75, v90 row_newbcast:6 row_mask:0xf bank_mask:0xf
	v_fmac_f32_dpp v59, v75, v90 row_newbcast:7 row_mask:0xf bank_mask:0xf
	v_fmac_f32_dpp v56, v79, v88 row_newbcast:4 row_mask:0xf bank_mask:0xf
	v_fmac_f32_dpp v57, v79, v88 row_newbcast:5 row_mask:0xf bank_mask:0xf
	v_fmac_f32_dpp v58, v79, v88 row_newbcast:6 row_mask:0xf bank_mask:0xf
	v_fmac_f32_dpp v59, v79, v88 row_newbcast:7 row_mask:0xf bank_mask:0xf
	v_fmac_f32_dpp v94, v83, v56 row_newbcast:4 row_mask:0xf bank_mask:0xf
	v_fmac_f32_dpp v95, v83, v57 row_newbcast:5 row_mask:0xf bank_mask:0xf
	v_fmac_f32_dpp v96, v83, v58 row_newbcast:6 row_mask:0xf bank_mask:0xf
	v_fmac_f32_dpp v97, v83, v59 row_newbcast:7 row_mask:0xf bank_mask:0xf
	v_mul_f32_dpp v52, v71, v52 row_newbcast:8 row_mask:0xf bank_mask:0xf
	v_mul_f32_dpp v53, v71, v53 row_newbcast:9 row_mask:0xf bank_mask:0xf
	v_mul_f32_dpp v54, v71, v54 row_newbcast:10 row_mask:0xf bank_mask:0xf
	v_mul_f32_dpp v55, v71, v55 row_newbcast:11 row_mask:0xf bank_mask:0xf
	v_fmac_f32_dpp v52, v75, v90 row_newbcast:8 row_mask:0xf bank_mask:0xf
	v_fmac_f32_dpp v53, v75, v90 row_newbcast:9 row_mask:0xf bank_mask:0xf
	v_fmac_f32_dpp v54, v75, v90 row_newbcast:10 row_mask:0xf bank_mask:0xf
	v_fmac_f32_dpp v55, v75, v90 row_newbcast:11 row_mask:0xf bank_mask:0xf
	v_fmac_f32_dpp v52, v79, v88 row_newbcast:8 row_mask:0xf bank_mask:0xf
	v_fmac_f32_dpp v53, v79, v88 row_newbcast:9 row_mask:0xf bank_mask:0xf
	v_fmac_f32_dpp v54, v79, v88 row_newbcast:10 row_mask:0xf bank_mask:0xf
	v_fmac_f32_dpp v55, v79, v88 row_newbcast:11 row_mask:0xf bank_mask:0xf
	v_fmac_f32_dpp v94, v83, v52 row_newbcast:8 row_mask:0xf bank_mask:0xf
	v_fmac_f32_dpp v95, v83, v53 row_newbcast:9 row_mask:0xf bank_mask:0xf
	v_fmac_f32_dpp v96, v83, v54 row_newbcast:10 row_mask:0xf bank_mask:0xf
	v_fmac_f32_dpp v97, v83, v55 row_newbcast:11 row_mask:0xf bank_mask:0xf
	v_mul_f32_dpp v48, v71, v48 row_newbcast:12 row_mask:0xf bank_mask:0xf
	v_mul_f32_dpp v49, v71, v49 row_newbcast:13 row_mask:0xf bank_mask:0xf
	v_mul_f32_dpp v50, v71, v50 row_newbcast:14 row_mask:0xf bank_mask:0xf
	v_mul_f32_dpp v51, v71, v51 row_newbcast:15 row_mask:0xf bank_mask:0xf
	v_fmac_f32_dpp v48, v75, v90 row_newbcast:12 row_mask:0xf bank_mask:0xf
	v_fmac_f32_dpp v49, v75, v90 row_newbcast:13 row_mask:0xf bank_mask:0xf
	v_fmac_f32_dpp v50, v75, v90 row_newbcast:14 row_mask:0xf bank_mask:0xf
	v_fmac_f32_dpp v51, v75, v90 row_newbcast:15 row_mask:0xf bank_mask:0xf
	v_fmac_f32_dpp v48, v79, v88 row_newbcast:12 row_mask:0xf bank_mask:0xf
	v_fmac_f32_dpp v49, v79, v88 row_newbcast:13 row_mask:0xf bank_mask:0xf
	v_fmac_f32_dpp v50, v79, v88 row_newbcast:14 row_mask:0xf bank_mask:0xf
	v_fmac_f32_dpp v51, v79, v88 row_newbcast:15 row_mask:0xf bank_mask:0xf
	v_fmac_f32_dpp v94, v83, v48 row_newbcast:12 row_mask:0xf bank_mask:0xf
	v_fmac_f32_dpp v95, v83, v49 row_newbcast:13 row_mask:0xf bank_mask:0xf
	v_fmac_f32_dpp v96, v83, v50 row_newbcast:14 row_mask:0xf bank_mask:0xf
	v_fmac_f32_dpp v97, v83, v51 row_newbcast:15 row_mask:0xf bank_mask:0xf
	ds_read_b32 v71, v100 offset:12480
	ds_read_b32 v75, v100 offset:16576
	ds_read_b32 v83, v100 offset:4288
	v_add_f32_e32 v94, v94, v95
	v_add_f32_e32 v96, v96, v97
	s_or_b32 s8, s14, s44
	s_ashr_i32 s9, s8, 31
	s_lshl_b64 s[8:9], s[8:9], 10
	v_add_f32_e32 v94, v94, v96
	s_add_i32 s4, s4, 1
	s_add_i32 s5, s5, -1
	v_lshl_add_u64 v[104:105], v[136:137], 0, s[8:9]
	v_cvt_pk_bf16_f32 v94, v94, v94
	s_cmp_eq_u32 s4, 16
	global_store_short v[104:105], v94, off
	s_cbranch_scc1 .Lscan_c_exit
	s_waitcnt vmcnt(1)
	v_mov_b32_e32 v76, v84
	v_mov_b32_e32 v77, v85
	v_mov_b32_e32 v78, v86
	v_mov_b32_e32 v79, v87
	v_mov_b32_e32 v88, v89
	s_branch .Lscan_c_step
.Lscan_c_exit:
	s_waitcnt vmcnt(1) lgkmcnt(0)
	s_branch .LBB0_548
